# v47 with s_sleep 0 instead of s_sleep 2 in the six hand-off poll loops (poll-loop tightening)
# baseline (speedup 1.0000x reference)
.LBB0_599:
	global_load_dword v5, v4, s[6:7] sc1
	s_mov_b64 s[24:25], -1
	s_mov_b64 s[26:27], -1
	s_waitcnt vmcnt(0)
	v_readfirstlane_b32 s1, v5
	s_cmp_gt_u32 s1, 3
	s_cbranch_scc1 .LBB0_598
	s_memrealtime s[24:25]
	s_waitcnt lgkmcnt(0)
	s_sub_u32 s24, s24, s18
	s_subb_u32 s25, s25, s19
	v_cmp_lt_u64_e32 vcc, s[24:25], v[2:3]
	s_cbranch_vccz .LBB0_597
	s_mov_b64 s[26:27], 0
	s_sleep 0
	s_branch .LBB0_597

.LBB0_641:
	global_load_dword v5, v4, s[14:15] sc1
	s_mov_b64 s[16:17], -1
	s_waitcnt vmcnt(0)
	v_readfirstlane_b32 s18, v5
	s_cmpk_gt_u32 s18, 0x7f
	s_mov_b64 s[18:19], -1
	s_cbranch_scc1 .LBB0_640
	s_memrealtime s[16:17]
	s_waitcnt lgkmcnt(0)
	s_sub_u32 s16, s16, s2
	s_subb_u32 s17, s17, s3
	v_cmp_lt_u64_e32 vcc, s[16:17], v[2:3]
	s_cbranch_vccz .LBB0_639
	s_mov_b64 s[18:19], 0
	s_sleep 0
	s_branch .LBB0_639

.LBB0_658:
	global_load_dword v5, v4, s[28:29] sc1
	s_mov_b64 s[30:31], -1
	s_mov_b64 s[34:35], -1
	s_waitcnt vmcnt(0)
	v_readfirstlane_b32 s1, v5
	s_cmp_gt_u32 s1, 3
	s_cbranch_scc1 .LBB0_657
	s_memrealtime s[30:31]
	s_waitcnt lgkmcnt(0)
	s_sub_u32 s30, s30, s6
	s_subb_u32 s31, s31, s7
	v_cmp_lt_u64_e32 vcc, s[30:31], v[2:3]
	s_cbranch_vccz .LBB0_656
	s_mov_b64 s[34:35], 0
	s_sleep 0
	s_branch .LBB0_656

.LBB0_715:
	global_load_dword v5, v4, s[20:21] sc1
	s_mov_b64 s[6:7], -1
	s_mov_b64 s[8:9], -1
	s_waitcnt vmcnt(0)
	v_readfirstlane_b32 s1, v5
	s_cmpk_gt_u32 s1, 0x7f
	s_cbranch_scc1 .LBB0_714
	s_memrealtime s[6:7]
	s_waitcnt lgkmcnt(0)
	s_sub_u32 s6, s6, s2
	s_subb_u32 s7, s7, s3
	v_cmp_lt_u64_e32 vcc, s[6:7], v[2:3]
	s_cbranch_vccz .LBB0_713
	s_mov_b64 s[8:9], 0
	s_sleep 0
	s_branch .LBB0_713

.LBB0_737:
	global_load_dword v5, v4, s[26:27] sc1
	s_mov_b64 s[8:9], -1
	s_mov_b64 s[20:21], -1
	s_waitcnt vmcnt(0)
	v_readfirstlane_b32 s1, v5
	s_cmp_gt_u32 s1, 3
	s_cbranch_scc1 .LBB0_736
	s_memrealtime s[8:9]
	s_waitcnt lgkmcnt(0)
	s_sub_u32 s8, s8, s6
	s_subb_u32 s9, s9, s7
	v_cmp_lt_u64_e32 vcc, s[8:9], v[2:3]
	s_cbranch_vccz .LBB0_735
	s_mov_b64 s[20:21], 0
	s_sleep 0
	s_branch .LBB0_735

.LBB0_772:
	global_load_dword v4, v1, s[16:17] sc1
	s_mov_b64 s[4:5], -1
	s_waitcnt vmcnt(0)
	v_readfirstlane_b32 s6, v4
	s_cmpk_gt_u32 s6, 0x7f
	s_mov_b64 s[6:7], -1
	s_cbranch_scc1 .LBB0_771
	s_memrealtime s[4:5]
	s_waitcnt lgkmcnt(0)
	s_sub_u32 s4, s4, s2
	s_subb_u32 s5, s5, s3
	v_cmp_lt_u64_e32 vcc, s[4:5], v[2:3]
	s_cbranch_vccz .LBB0_770
	s_mov_b64 s[6:7], 0
	s_sleep 0
	s_branch .LBB0_770
